# out-proj epilogue chain runs at s_setprio 2 (reset to 0 after the last element), on top of v50
# speedup vs baseline: 1.0036x; 1.0036x over previous
; DI int crow(int i, int h) { return (i & 3) + 8 * (i >> 2) + 4 * h; }
; DI void phase_out(CP p, const Ptrs& w, int l, bf16_t* sA, bf16_t* sB) {
;     ...
;   for (int kk = 0; kk < nrounds; ++kk) {
;     ...
;         for (int i = 0; i < 16; ++i) {
;           int ii = ib + wm * 64 + mi * 32 + crow(i, h);
;           const float* src = xrow(p, w, l, b * TPB + ii);
;           float* dstp = isctx ? w.xc1 + (size_t)(b * CTXL + ii) * DM : p.out + (size_t)(b * 8192 + ii - CTXL) * DM;
;           dstp[col] = src[col] + gt * acc[mi][ni][i];
;         }
;       }
;   }
.LBB0_947:
	v_ashrrev_i32_e32 v1, 31, v0
	v_lshlrev_b64 v[0:1], 13, v[0:1]
	v_lshl_add_u64 v[0:1], v[2:3], 0, v[0:1]
	v_lshl_add_u64 v[0:1], v[64:65], 2, v[0:1]
	global_load_dword v0, v[0:1], off offset:128
	s_waitcnt vmcnt(0)
	v_fmac_f32_e32 v0, v15, v52
	global_store_dword v[30:31], v0, off offset:128
	s_setprio 0
	s_add_i32 s17, s17, 1
	s_cmp_lg_u32 s17, s42
	s_mov_b32 s10, s16
	s_cbranch_scc0 .LBB0_1727

; DI int crow(int i, int h) { return (i & 3) + 8 * (i >> 2) + 4 * h; }
; DI void phase_out(CP p, const Ptrs& w, int l, bf16_t* sA, bf16_t* sB) {
;     ...
;     int b = m0 / TPB, ib = m0 - b * TPB;
;     bool isctx = ib < CTXL;
;     f32x16 acc[2][2];
;     zero_acc(acc);
;     gemm_128_deep(w.R2 + (size_t)m0 * 2048, 2048, out_t + (size_t)n0 * 2048, 2048, 2048, acc, sA, sB);
;     const float* gate = w.mod + (l * 3 + (isctx ? 2 : b)) * 6144 + 4096;
; #pragma unroll
;     for (int mi = 0; mi < 2; ++mi)
; #pragma unroll
;       for (int ni = 0; ni < 2; ++ni) {
;         int col = n0 + wn * 64 + ni * 32 + r;
;         float gt = gate[col];
; #pragma unroll
;         for (int i = 0; i < 16; ++i) {
;           int ii = ib + wm * 64 + mi * 32 + crow(i, h);
;           const float* src = xrow(p, w, l, b * TPB + ii);
;           float* dstp = isctx ? w.xc1 + (size_t)(b * CTXL + ii) * DM : p.out + (size_t)(b * 8192 + ii - CTXL) * DM;
;           dstp[col] = src[col] + gt * acc[mi][ni][i];
;         }
;       }
.LBB0_967:
	s_lshl_b32 s10, s39, 13
	s_addk_i32 s10, 0xff00
	s_lshl_b32 s11, s39, 8
	v_ashrrev_i32_e32 v67, 31, v66
	s_and_b64 s[4:5], s[4:5], exec
	v_lshlrev_b64 v[66:67], 13, v[66:67]
	s_cselect_b32 s39, s11, s10
	v_lshl_add_u64 v[70:71], v[70:71], 0, v[66:67]
	v_add_u32_e32 v66, s39, v72
	v_ashrrev_i32_e32 v67, 31, v66
	s_cselect_b32 s5, s13, s77
	s_cselect_b32 s4, s12, s76
	v_lshlrev_b64 v[66:67], 13, v[66:67]
	v_lshl_add_u64 v[72:73], s[4:5], 0, v[66:67]
	v_lshlrev_b64 v[66:67], 2, v[64:65]
	v_lshl_add_u64 v[70:71], v[70:71], 0, v[66:67]
	s_nop 0
	v_readfirstlane_b32 s100, v70
	v_readfirstlane_b32 s101, v71
	v_mbcnt_lo_u32_b32 v168, -1, 0
	v_mbcnt_hi_u32_b32 v168, -1, v168
	v_lshlrev_b32_e32 v168, 13, v168
	s_nop 2
	global_load_dword v169, v168, s[100:101]
	global_load_dword v169, v168, s[100:101] offset:128
	s_setprio 2
	v_subrev_u32_e32 v170, s100, v70
	global_load_dword v194, v170, s[100:101]
	v_add_u32_e32 v171, 0x2000, v170
	global_load_dword v195, v171, s[100:101]
	v_add_u32_e32 v171, 0x4000, v170
	global_load_dword v196, v171, s[100:101]
	v_add_u32_e32 v171, 0x6000, v170
	global_load_dword v197, v171, s[100:101]
	v_add_u32_e32 v171, 0x10000, v170
	global_load_dword v198, v171, s[100:101]
	v_add_u32_e32 v171, 0x12000, v170
	global_load_dword v199, v171, s[100:101]
	v_add_u32_e32 v171, 0x14000, v170
	global_load_dword v200, v171, s[100:101]
	v_add_u32_e32 v171, 0x16000, v170
	global_load_dword v201, v171, s[100:101]
	v_add_u32_e32 v171, 0x20000, v170
	global_load_dword v202, v171, s[100:101]
	v_add_u32_e32 v171, 0x22000, v170
	global_load_dword v203, v171, s[100:101]
	v_add_u32_e32 v171, 0x24000, v170
	global_load_dword v204, v171, s[100:101]
	v_add_u32_e32 v171, 0x26000, v170
	global_load_dword v205, v171, s[100:101]
	v_add_u32_e32 v171, 0x30000, v170
	global_load_dword v206, v171, s[100:101]
	v_add_u32_e32 v171, 0x32000, v170
	global_load_dword v207, v171, s[100:101]
	v_add_u32_e32 v171, 0x34000, v170
	global_load_dword v208, v171, s[100:101]
	v_add_u32_e32 v171, 0x36000, v170
	global_load_dword v209, v171, s[100:101]
	v_add_u32_e32 v171, 0x80, v170
	global_load_dword v210, v171, s[100:101]
	v_add_u32_e32 v171, 0x2080, v170
	global_load_dword v211, v171, s[100:101]
	v_add_u32_e32 v171, 0x4080, v170
	global_load_dword v212, v171, s[100:101]
	v_add_u32_e32 v171, 0x6080, v170
	global_load_dword v213, v171, s[100:101]
	v_add_u32_e32 v171, 0x10080, v170
	global_load_dword v172, v171, s[100:101]
	v_add_u32_e32 v171, 0x12080, v170
	global_load_dword v173, v171, s[100:101]
	v_add_u32_e32 v171, 0x14080, v170
	global_load_dword v174, v171, s[100:101]
	v_add_u32_e32 v171, 0x16080, v170
	global_load_dword v175, v171, s[100:101]
	v_add_u32_e32 v171, 0x20080, v170
	global_load_dword v176, v171, s[100:101]
	v_add_u32_e32 v171, 0x22080, v170
	global_load_dword v177, v171, s[100:101]
	v_add_u32_e32 v171, 0x24080, v170
	global_load_dword v178, v171, s[100:101]
	v_add_u32_e32 v171, 0x26080, v170
	global_load_dword v179, v171, s[100:101]
	v_add_u32_e32 v171, 0x30080, v170
	global_load_dword v132, v171, s[100:101]
	v_add_u32_e32 v171, 0x32080, v170
	global_load_dword v133, v171, s[100:101]
	v_add_u32_e32 v171, 0x34080, v170
	global_load_dword v134, v171, s[100:101]
	v_add_u32_e32 v171, 0x36080, v170
	global_load_dword v135, v171, s[100:101]
	v_lshl_add_u64 v[70:71], v[72:73], 0, v[66:67]
	v_readlane_b32 s46, v254, 54
	v_readlane_b32 s47, v254, 55
	s_mov_b64 s[10:11], -1
	s_andn2_b64 vcc, exec, s[46:47]
	s_waitcnt vmcnt(31)
	v_fma_f32 v74, v48, v90, v194
	v_or_b32_e32 v48, v92, v167
	v_add_u32_e32 v72, s38, v48
	v_mul_hi_i32 v73, v72, s0
	global_store_dword v[70:71], v74, off
	v_lshrrev_b32_e32 v74, 31, v73
	v_ashrrev_i32_e32 v73, 11, v73
	v_add_u32_e32 v95, v73, v74
	v_mad_i32_i24 v96, v95, s1, v72
	v_cndmask_b32_e64 v72, 0, 1, s[46:47]
	v_cmp_lt_i32_e64 s[44:45], s37, v96
	v_cmp_ne_u32_e64 s[40:41], 1, v72
	v_add_u32_e32 v74, s39, v48
	v_ashrrev_i32_e32 v75, 31, v74
	v_lshlrev_b64 v[74:75], 13, v[74:75]
	v_lshl_add_u64 v[74:75], s[4:5], 0, v[74:75]
	v_lshl_add_u64 v[72:73], v[74:75], 0, v[66:67]
	v_or_b32_e32 v76, v92, v180
	s_mov_b64 s[10:11], -1
	s_and_b64 vcc, exec, s[40:41]
	s_waitcnt vmcnt(31)
	v_fma_f32 v48, v49, v90, v195
	global_store_dword v[72:73], v48, off
	v_add_u32_e32 v48, s38, v76
	v_mul_hi_i32 v49, v48, s0
	v_lshrrev_b32_e32 v74, 31, v49
	v_ashrrev_i32_e32 v49, 11, v49
	v_add_u32_e32 v97, v49, v74
	v_mad_i32_i24 v98, v97, s1, v48
	v_cmp_lt_i32_e64 s[46:47], s37, v98
	v_add_u32_e32 v74, s39, v76
	v_ashrrev_i32_e32 v75, 31, v74
	v_lshlrev_b64 v[74:75], 13, v[74:75]
	v_lshl_add_u64 v[74:75], s[4:5], 0, v[74:75]
	v_lshl_add_u64 v[74:75], v[74:75], 0, v[66:67]
	s_mov_b64 s[10:11], -1
	s_and_b64 vcc, exec, s[40:41]
	s_waitcnt vmcnt(31)
	v_fma_f32 v48, v50, v90, v196
	v_or_b32_e32 v50, v92, v181
	global_store_dword v[74:75], v48, off
	v_add_u32_e32 v48, s38, v50
	v_mul_hi_i32 v49, v48, s0
	v_lshrrev_b32_e32 v76, 31, v49
	v_ashrrev_i32_e32 v49, 11, v49
	v_add_u32_e32 v99, v49, v76
	v_mad_i32_i24 v100, v99, s1, v48
	v_cmp_lt_i32_e64 s[48:49], s37, v100
	v_add_u32_e32 v76, s39, v50
	v_ashrrev_i32_e32 v77, 31, v76
	v_lshlrev_b64 v[76:77], 13, v[76:77]
	v_lshl_add_u64 v[76:77], s[4:5], 0, v[76:77]
	v_or_b32_e32 v78, v92, v182
	s_mov_b64 s[10:11], -1
	s_and_b64 vcc, exec, s[40:41]
	s_waitcnt vmcnt(31)
	v_fma_f32 v48, v51, v90, v197
	v_lshl_add_u64 v[50:51], v[76:77], 0, v[66:67]
	global_store_dword v[50:51], v48, off
	v_add_u32_e32 v48, s38, v78
	v_mul_hi_i32 v49, v48, s0
	v_lshrrev_b32_e32 v76, 31, v49
	v_ashrrev_i32_e32 v49, 11, v49
	v_add_u32_e32 v101, v49, v76
	v_mad_i32_i24 v102, v101, s1, v48
	v_cmp_lt_i32_e64 s[50:51], s37, v102
	v_add_u32_e32 v76, s39, v78
	v_ashrrev_i32_e32 v77, 31, v76
	v_lshlrev_b64 v[76:77], 13, v[76:77]
	v_lshl_add_u64 v[76:77], s[4:5], 0, v[76:77]
	v_lshl_add_u64 v[76:77], v[76:77], 0, v[66:67]
	s_mov_b64 s[10:11], -1
	s_and_b64 vcc, exec, s[40:41]
	s_waitcnt vmcnt(31)
; DI int crow(int i, int h) { return (i & 3) + 8 * (i >> 2) + 4 * h; }
; DI void phase_out(CP p, const Ptrs& w, int l, bf16_t* sA, bf16_t* sB) {
;     ...
;       for (int ni = 0; ni < 2; ++ni) {
;         int col = n0 + wn * 64 + ni * 32 + r;
;         float gt = gate[col];
; #pragma unroll
;         for (int i = 0; i < 16; ++i) {
;           int ii = ib + wm * 64 + mi * 32 + crow(i, h);
;           const float* src = xrow(p, w, l, b * TPB + ii);
;           float* dstp = isctx ? w.xc1 + (size_t)(b * CTXL + ii) * DM : p.out + (size_t)(b * 8192 + ii - CTXL) * DM;
;           dstp[col] = src[col] + gt * acc[mi][ni][i];
;         }
;       }
	v_fma_f32 v48, v52, v90, v198
	v_or_b32_e32 v52, v92, v183
	global_store_dword v[76:77], v48, off
	v_add_u32_e32 v48, s38, v52
	v_mul_hi_i32 v49, v48, s0
	v_lshrrev_b32_e32 v78, 31, v49
	v_ashrrev_i32_e32 v49, 11, v49
	v_add_u32_e32 v103, v49, v78
	v_mad_i32_i24 v104, v103, s1, v48
	v_cmp_lt_i32_e64 s[52:53], s37, v104
	v_add_u32_e32 v78, s39, v52
	v_ashrrev_i32_e32 v79, 31, v78
	v_lshlrev_b64 v[78:79], 13, v[78:79]
	v_lshl_add_u64 v[78:79], s[4:5], 0, v[78:79]
	v_or_b32_e32 v80, v92, v184
	s_mov_b64 s[10:11], -1
	s_and_b64 vcc, exec, s[40:41]
	s_waitcnt vmcnt(31)
	v_fma_f32 v48, v53, v90, v199
	v_lshl_add_u64 v[52:53], v[78:79], 0, v[66:67]
	global_store_dword v[52:53], v48, off
	v_add_u32_e32 v48, s38, v80
	v_mul_hi_i32 v49, v48, s0
	v_lshrrev_b32_e32 v78, 31, v49
	v_ashrrev_i32_e32 v49, 11, v49
	v_add_u32_e32 v105, v49, v78
	v_mad_i32_i24 v106, v105, s1, v48
	v_cmp_lt_i32_e64 s[54:55], s37, v106
	v_add_u32_e32 v78, s39, v80
	v_ashrrev_i32_e32 v79, 31, v78
	v_lshlrev_b64 v[78:79], 13, v[78:79]
	v_lshl_add_u64 v[78:79], s[4:5], 0, v[78:79]
	v_lshl_add_u64 v[78:79], v[78:79], 0, v[66:67]
	s_mov_b64 s[10:11], -1
	s_and_b64 vcc, exec, s[40:41]
	s_waitcnt vmcnt(31)
	v_fma_f32 v48, v54, v90, v200
	v_or_b32_e32 v54, v92, v185
	global_store_dword v[78:79], v48, off
	v_add_u32_e32 v48, s38, v54
	v_mul_hi_i32 v49, v48, s0
	v_lshrrev_b32_e32 v80, 31, v49
	v_ashrrev_i32_e32 v49, 11, v49
	v_add_u32_e32 v107, v49, v80
	v_mad_i32_i24 v108, v107, s1, v48
	v_cmp_lt_i32_e64 s[56:57], s37, v108
	v_add_u32_e32 v80, s39, v54
	v_ashrrev_i32_e32 v81, 31, v80
	v_lshlrev_b64 v[80:81], 13, v[80:81]
	v_lshl_add_u64 v[80:81], s[4:5], 0, v[80:81]
	v_or_b32_e32 v82, v92, v186
	s_mov_b64 s[10:11], -1
	s_and_b64 vcc, exec, s[40:41]
	s_waitcnt vmcnt(31)
	v_fma_f32 v48, v55, v90, v201
	v_lshl_add_u64 v[54:55], v[80:81], 0, v[66:67]
	global_store_dword v[54:55], v48, off
	v_add_u32_e32 v48, s38, v82
	v_mul_hi_i32 v49, v48, s0
	v_lshrrev_b32_e32 v80, 31, v49
	v_ashrrev_i32_e32 v49, 11, v49
	v_add_u32_e32 v109, v49, v80
	v_mad_i32_i24 v110, v109, s1, v48
	v_cmp_lt_i32_e64 s[58:59], s37, v110
	v_add_u32_e32 v80, s39, v82
	v_ashrrev_i32_e32 v81, 31, v80
	v_lshlrev_b64 v[80:81], 13, v[80:81]
	v_lshl_add_u64 v[80:81], s[4:5], 0, v[80:81]
	v_lshl_add_u64 v[80:81], v[80:81], 0, v[66:67]
	s_mov_b64 s[10:11], -1
	s_and_b64 vcc, exec, s[40:41]
	s_waitcnt vmcnt(31)
	v_fma_f32 v48, v56, v90, v202
	v_or_b32_e32 v56, v92, v187
	global_store_dword v[80:81], v48, off
	v_add_u32_e32 v48, s38, v56
	v_mul_hi_i32 v49, v48, s0
	v_lshrrev_b32_e32 v82, 31, v49
	v_ashrrev_i32_e32 v49, 11, v49
	v_add_u32_e32 v111, v49, v82
	v_mad_i32_i24 v112, v111, s1, v48
	v_cmp_lt_i32_e64 s[60:61], s37, v112
	v_add_u32_e32 v82, s39, v56
	v_ashrrev_i32_e32 v83, 31, v82
	v_lshlrev_b64 v[82:83], 13, v[82:83]
	v_lshl_add_u64 v[82:83], s[4:5], 0, v[82:83]
	v_or_b32_e32 v84, v92, v188
	s_mov_b64 s[10:11], -1
	s_and_b64 vcc, exec, s[40:41]
	s_waitcnt vmcnt(31)
	v_fma_f32 v48, v57, v90, v203
	v_lshl_add_u64 v[56:57], v[82:83], 0, v[66:67]
	global_store_dword v[56:57], v48, off
	v_add_u32_e32 v48, s38, v84
	v_mul_hi_i32 v49, v48, s0
	v_lshrrev_b32_e32 v82, 31, v49
	v_ashrrev_i32_e32 v49, 11, v49
	v_add_u32_e32 v113, v49, v82
	v_mad_i32_i24 v114, v113, s1, v48
	v_cmp_lt_i32_e64 s[62:63], s37, v114
	v_add_u32_e32 v82, s39, v84
	v_ashrrev_i32_e32 v83, 31, v82
	v_lshlrev_b64 v[82:83], 13, v[82:83]
	v_lshl_add_u64 v[82:83], s[4:5], 0, v[82:83]
	v_lshl_add_u64 v[82:83], v[82:83], 0, v[66:67]
	s_mov_b64 s[10:11], -1
	s_and_b64 vcc, exec, s[40:41]
	s_waitcnt vmcnt(31)
	v_fma_f32 v48, v58, v90, v204
	v_or_b32_e32 v58, v92, v189
	global_store_dword v[82:83], v48, off
	v_add_u32_e32 v48, s38, v58
	v_mul_hi_i32 v49, v48, s0
	v_lshrrev_b32_e32 v84, 31, v49
	v_ashrrev_i32_e32 v49, 11, v49
	v_add_u32_e32 v115, v49, v84
	v_mad_i32_i24 v116, v115, s1, v48
	v_cmp_lt_i32_e64 s[64:65], s37, v116
	v_add_u32_e32 v84, s39, v58
	v_ashrrev_i32_e32 v85, 31, v84
	v_lshlrev_b64 v[84:85], 13, v[84:85]
	v_lshl_add_u64 v[84:85], s[4:5], 0, v[84:85]
	v_or_b32_e32 v86, v92, v190
	s_mov_b64 s[10:11], -1
	s_and_b64 vcc, exec, s[40:41]
	s_waitcnt vmcnt(31)
	v_fma_f32 v48, v59, v90, v205
	v_lshl_add_u64 v[58:59], v[84:85], 0, v[66:67]
	global_store_dword v[58:59], v48, off
	v_add_u32_e32 v48, s38, v86
	v_mul_hi_i32 v49, v48, s0
	v_lshrrev_b32_e32 v84, 31, v49
	v_ashrrev_i32_e32 v49, 11, v49
	v_add_u32_e32 v117, v49, v84
	v_mad_i32_i24 v118, v117, s1, v48
	v_cmp_lt_i32_e64 s[66:67], s37, v118
	v_add_u32_e32 v84, s39, v86
	v_ashrrev_i32_e32 v85, 31, v84
	v_lshlrev_b64 v[84:85], 13, v[84:85]
	v_lshl_add_u64 v[84:85], s[4:5], 0, v[84:85]
	v_lshl_add_u64 v[84:85], v[84:85], 0, v[66:67]
	s_mov_b64 s[10:11], -1
	s_and_b64 vcc, exec, s[40:41]
	s_waitcnt vmcnt(31)
	v_fma_f32 v48, v60, v90, v206
	v_or_b32_e32 v60, v92, v191
	global_store_dword v[84:85], v48, off
	v_add_u32_e32 v48, s38, v60
	v_mul_hi_i32 v49, v48, s0
	v_lshrrev_b32_e32 v86, 31, v49
	v_ashrrev_i32_e32 v49, 11, v49
	v_add_u32_e32 v119, v49, v86
	v_mad_i32_i24 v120, v119, s1, v48
	v_cmp_lt_i32_e64 s[68:69], s37, v120
	v_add_u32_e32 v86, s39, v60
	v_ashrrev_i32_e32 v87, 31, v86
	v_lshlrev_b64 v[86:87], 13, v[86:87]
	v_lshl_add_u64 v[86:87], s[4:5], 0, v[86:87]
	v_or_b32_e32 v88, v92, v192
	s_mov_b64 s[10:11], -1
	s_and_b64 vcc, exec, s[40:41]
	s_waitcnt vmcnt(31)
	v_fma_f32 v48, v61, v90, v207
	v_lshl_add_u64 v[60:61], v[86:87], 0, v[66:67]
	global_store_dword v[60:61], v48, off
	v_add_u32_e32 v48, s38, v88
	v_mul_hi_i32 v49, v48, s0
	v_lshrrev_b32_e32 v86, 31, v49
	v_ashrrev_i32_e32 v49, 11, v49
	v_add_u32_e32 v121, v49, v86
	v_mad_i32_i24 v122, v121, s1, v48
	v_cmp_lt_i32_e64 s[70:71], s37, v122
	v_add_u32_e32 v86, s39, v88
	v_ashrrev_i32_e32 v87, 31, v86
	v_lshlrev_b64 v[86:87], 13, v[86:87]
	v_lshl_add_u64 v[86:87], s[4:5], 0, v[86:87]
	v_lshl_add_u64 v[86:87], v[86:87], 0, v[66:67]
	s_mov_b64 s[10:11], -1
	s_and_b64 vcc, exec, s[40:41]
	s_waitcnt vmcnt(31)
	v_fma_f32 v48, v62, v90, v208
	v_or_b32_e32 v62, v92, v193
	global_store_dword v[86:87], v48, off
	v_add_u32_e32 v48, s38, v62
	v_mul_hi_i32 v49, v48, s0
	v_lshrrev_b32_e32 v88, 31, v49
	v_ashrrev_i32_e32 v49, 11, v49
	v_add_u32_e32 v123, v49, v88
	v_mad_i32_i24 v124, v123, s1, v48
	v_cmp_lt_i32_e64 s[72:73], s37, v124
	s_cbranch_vccnz .LBB0_1141
	s_and_saveexec_b64 s[10:11], s[72:73]
	s_xor_b64 s[10:11], exec, s[10:11]
	v_lshlrev_b32_e32 v48, 13, v123
	s_movk_i32 vcc_lo, 0xff00
	v_add3_u32 v48, v48, v124, vcc_lo
	s_or_saveexec_b64 s[10:11], s[10:11]
	v_mov_b64_e32 v[88:89], s[76:77]
	s_xor_b64 exec, exec, s[10:11]
	v_lshl_add_u32 v48, v123, 8, v124
	v_mov_b64_e32 v[88:89], s[12:13]
	s_or_b64 exec, exec, s[10:11]
	s_mov_b64 s[10:11], 0
